# v27_loopalign
# speedup vs baseline: 1.0191x; 1.0019x over previous
; template <class Epi, class Sched, bool F8 = false>
; __device__ __forceinline__ void gemm_phase(LAS unsigned char* lds, const int lda, const int ldb, const Sched& S, const Epi& E) {
;     ...
;         for (int t = 0; t < nt; t += 2) {
;             const bool last = (t == nt - 2);
;             const char* a1 = cA + (size_t)(t + 1) * kstep;
;             const char* a2 = last ? nA : cA + (size_t)(t + 2) * kstep; const char* b2 = last ? nB : cB + (size_t)(t + 2) * kstepB;
;             const char* a3 = a2 + kstep; const char* b3 = b2 + kstepB;
;     ...
;         if (!(Epi::KEEP && cur.kind == 0)) {
; #pragma unroll
;         for (int a = 0; a < 2; ++a)
; #pragma unroll
;             for (int b = 0; b < 2; ++b)
; #pragma unroll
;                 for (int m = 0; m < 4; ++m)
; #pragma unroll
;                     for (int n = 0; n < 2; ++n) acc[a][b][m][n] = (f32x4){0.f, 0.f, 0.f, 0.f};
;         }
;         cur = nxt; cA = nA; cB = nB; ++ui;
.LBB0_115:
	s_add_u32 s7, s22, 0x10000
	s_addc_u32 s62, s23, 0
	s_add_u32 s63, s20, 0x100080
	v_mov_b32_e32 v0, 0
	s_addc_u32 s67, s21, 0
	s_mov_b32 s69, -2
	v_mov_b32_e32 v1, v0
	v_mov_b32_e32 v2, v0
	v_mov_b32_e32 v3, v0
	v_mov_b32_e32 v4, v0
	v_mov_b32_e32 v5, v0
	v_mov_b32_e32 v6, v0
	v_mov_b32_e32 v7, v0
	v_mov_b32_e32 v16, v0
	v_mov_b32_e32 v17, v0
	v_mov_b32_e32 v18, v0
	v_mov_b32_e32 v19, v0
	v_mov_b32_e32 v20, v0
	v_mov_b32_e32 v21, v0
	v_mov_b32_e32 v22, v0
	v_mov_b32_e32 v23, v0
	v_mov_b32_e32 v32, v0
	v_mov_b32_e32 v33, v0
	v_mov_b32_e32 v34, v0
	v_mov_b32_e32 v35, v0
	v_mov_b32_e32 v36, v0
	v_mov_b32_e32 v37, v0
	v_mov_b32_e32 v38, v0
	v_mov_b32_e32 v39, v0
	v_mov_b32_e32 v48, v0
	v_mov_b32_e32 v49, v0
	v_mov_b32_e32 v50, v0
	v_mov_b32_e32 v51, v0
	v_mov_b32_e32 v52, v0
	v_mov_b32_e32 v53, v0
	v_mov_b32_e32 v54, v0
	v_mov_b32_e32 v55, v0
	v_mov_b32_e32 v8, v0
	v_mov_b32_e32 v9, v0
	v_mov_b32_e32 v10, v0
	v_mov_b32_e32 v11, v0
	v_mov_b32_e32 v12, v0
	v_mov_b32_e32 v13, v0
	v_mov_b32_e32 v14, v0
	v_mov_b32_e32 v15, v0
	v_mov_b32_e32 v24, v0
	v_mov_b32_e32 v25, v0
	v_mov_b32_e32 v26, v0
	v_mov_b32_e32 v27, v0
	v_mov_b32_e32 v28, v0
	v_mov_b32_e32 v29, v0
	v_mov_b32_e32 v30, v0
	v_mov_b32_e32 v31, v0
	v_mov_b32_e32 v40, v0
	v_mov_b32_e32 v41, v0
	v_mov_b32_e32 v42, v0
	v_mov_b32_e32 v43, v0
	v_mov_b32_e32 v44, v0
	v_mov_b32_e32 v45, v0
	v_mov_b32_e32 v46, v0
	v_mov_b32_e32 v47, v0
	v_mov_b32_e32 v56, v0
	v_mov_b32_e32 v57, v0
	v_mov_b32_e32 v58, v0
	v_mov_b32_e32 v59, v0
	v_mov_b32_e32 v60, v0
	v_mov_b32_e32 v61, v0
	v_mov_b32_e32 v62, v0
	v_mov_b32_e32 v63, v0
	v_mov_b32_e32 v64, v0
	v_mov_b32_e32 v65, v0
	v_mov_b32_e32 v66, v0
	v_mov_b32_e32 v67, v0
	v_mov_b32_e32 v68, v0
	v_mov_b32_e32 v69, v0
	v_mov_b32_e32 v70, v0
	v_mov_b32_e32 v71, v0
	v_mov_b32_e32 v80, v0
	v_mov_b32_e32 v81, v0
	v_mov_b32_e32 v82, v0
	v_mov_b32_e32 v83, v0
	v_mov_b32_e32 v84, v0
	v_mov_b32_e32 v85, v0
	v_mov_b32_e32 v86, v0
	v_mov_b32_e32 v87, v0
	v_mov_b32_e32 v96, v0
	v_mov_b32_e32 v97, v0
	v_mov_b32_e32 v98, v0
	v_mov_b32_e32 v99, v0
	v_mov_b32_e32 v100, v0
	v_mov_b32_e32 v101, v0
	v_mov_b32_e32 v102, v0
	v_mov_b32_e32 v103, v0
	v_mov_b32_e32 v112, v0
	v_mov_b32_e32 v113, v0
	v_mov_b32_e32 v114, v0
	v_mov_b32_e32 v115, v0
	v_mov_b32_e32 v116, v0
	v_mov_b32_e32 v117, v0
	v_mov_b32_e32 v118, v0
	v_mov_b32_e32 v119, v0
	v_mov_b32_e32 v72, v0
	v_mov_b32_e32 v73, v0
	v_mov_b32_e32 v74, v0
	v_mov_b32_e32 v75, v0
	v_mov_b32_e32 v76, v0
	v_mov_b32_e32 v77, v0
	v_mov_b32_e32 v78, v0
	v_mov_b32_e32 v79, v0
	v_mov_b32_e32 v88, v0
	v_mov_b32_e32 v89, v0
	v_mov_b32_e32 v90, v0
	v_mov_b32_e32 v91, v0
	v_mov_b32_e32 v92, v0
	v_mov_b32_e32 v93, v0
	v_mov_b32_e32 v94, v0
	v_mov_b32_e32 v95, v0
	v_mov_b32_e32 v104, v0
	v_mov_b32_e32 v105, v0
	v_mov_b32_e32 v106, v0
	v_mov_b32_e32 v107, v0
	v_mov_b32_e32 v108, v0
	v_mov_b32_e32 v109, v0
	v_mov_b32_e32 v110, v0
	v_mov_b32_e32 v111, v0
	v_mov_b32_e32 v120, v0
	v_mov_b32_e32 v121, v0
	v_mov_b32_e32 v122, v0
	v_mov_b32_e32 v123, v0
	v_mov_b32_e32 v124, v0
	v_mov_b32_e32 v125, v0
	v_mov_b32_e32 v126, v0
	v_mov_b32_e32 v127, v0
	.p2align	6

; template <class Epi, class Sched, bool F8 = false>
; __device__ __forceinline__ void gemm_phase(LAS unsigned char* lds, const int lda, const int ldb, const Sched& S, const Epi& E) {
;     ...
;         for (int t = 0; t < nt; t += 2) {
;             const bool last = (t == nt - 2);
;             const char* a1 = cA + (size_t)(t + 1) * kstep;
;             const char* a2 = last ? nA : cA + (size_t)(t + 2) * kstep; const char* b2 = last ? nB : cB + (size_t)(t + 2) * kstepB;
;             const char* a3 = a2 + kstep; const char* b3 = b2 + kstepB;
;     ...
;         if (!(Epi::KEEP && cur.kind == 0)) {
; #pragma unroll
;         for (int a = 0; a < 2; ++a)
; #pragma unroll
;             for (int b = 0; b < 2; ++b)
; #pragma unroll
;                 for (int m = 0; m < 4; ++m)
; #pragma unroll
;                     for (int n = 0; n < 2; ++n) acc[a][b][m][n] = (f32x4){0.f, 0.f, 0.f, 0.f};
;         }
;         cur = nxt; cA = nA; cB = nB; ++ui;
.LBB0_173:
	s_add_u32 s7, s22, 0x10000
	s_addc_u32 s62, s23, 0
	s_add_u32 s63, s20, 0x80080
	v_mov_b32_e32 v0, 0
	s_addc_u32 s67, s21, 0
	s_mov_b32 s69, -2
	v_mov_b32_e32 v1, v0
	v_mov_b32_e32 v2, v0
	v_mov_b32_e32 v3, v0
	v_mov_b32_e32 v4, v0
	v_mov_b32_e32 v5, v0
	v_mov_b32_e32 v6, v0
	v_mov_b32_e32 v7, v0
	v_mov_b32_e32 v16, v0
	v_mov_b32_e32 v17, v0
	v_mov_b32_e32 v18, v0
	v_mov_b32_e32 v19, v0
	v_mov_b32_e32 v20, v0
	v_mov_b32_e32 v21, v0
	v_mov_b32_e32 v22, v0
	v_mov_b32_e32 v23, v0
	v_mov_b32_e32 v32, v0
	v_mov_b32_e32 v33, v0
	v_mov_b32_e32 v34, v0
	v_mov_b32_e32 v35, v0
	v_mov_b32_e32 v36, v0
	v_mov_b32_e32 v37, v0
	v_mov_b32_e32 v38, v0
	v_mov_b32_e32 v39, v0
	v_mov_b32_e32 v48, v0
	v_mov_b32_e32 v49, v0
	v_mov_b32_e32 v50, v0
	v_mov_b32_e32 v51, v0
	v_mov_b32_e32 v52, v0
	v_mov_b32_e32 v53, v0
	v_mov_b32_e32 v54, v0
	v_mov_b32_e32 v55, v0
	v_mov_b32_e32 v8, v0
	v_mov_b32_e32 v9, v0
	v_mov_b32_e32 v10, v0
	v_mov_b32_e32 v11, v0
	v_mov_b32_e32 v12, v0
	v_mov_b32_e32 v13, v0
	v_mov_b32_e32 v14, v0
	v_mov_b32_e32 v15, v0
	v_mov_b32_e32 v24, v0
	v_mov_b32_e32 v25, v0
	v_mov_b32_e32 v26, v0
	v_mov_b32_e32 v27, v0
	v_mov_b32_e32 v28, v0
	v_mov_b32_e32 v29, v0
	v_mov_b32_e32 v30, v0
	v_mov_b32_e32 v31, v0
	v_mov_b32_e32 v40, v0
	v_mov_b32_e32 v41, v0
	v_mov_b32_e32 v42, v0
	v_mov_b32_e32 v43, v0
	v_mov_b32_e32 v44, v0
	v_mov_b32_e32 v45, v0
	v_mov_b32_e32 v46, v0
	v_mov_b32_e32 v47, v0
	v_mov_b32_e32 v56, v0
	v_mov_b32_e32 v57, v0
	v_mov_b32_e32 v58, v0
	v_mov_b32_e32 v59, v0
	v_mov_b32_e32 v60, v0
	v_mov_b32_e32 v61, v0
	v_mov_b32_e32 v62, v0
	v_mov_b32_e32 v63, v0
	v_mov_b32_e32 v64, v0
	v_mov_b32_e32 v65, v0
	v_mov_b32_e32 v66, v0
	v_mov_b32_e32 v67, v0
	v_mov_b32_e32 v68, v0
	v_mov_b32_e32 v69, v0
	v_mov_b32_e32 v70, v0
	v_mov_b32_e32 v71, v0
	v_mov_b32_e32 v80, v0
	v_mov_b32_e32 v81, v0
	v_mov_b32_e32 v82, v0
	v_mov_b32_e32 v83, v0
	v_mov_b32_e32 v84, v0
	v_mov_b32_e32 v85, v0
	v_mov_b32_e32 v86, v0
	v_mov_b32_e32 v87, v0
	v_mov_b32_e32 v96, v0
	v_mov_b32_e32 v97, v0
	v_mov_b32_e32 v98, v0
	v_mov_b32_e32 v99, v0
	v_mov_b32_e32 v100, v0
	v_mov_b32_e32 v101, v0
	v_mov_b32_e32 v102, v0
	v_mov_b32_e32 v103, v0
	v_mov_b32_e32 v112, v0
	v_mov_b32_e32 v113, v0
	v_mov_b32_e32 v114, v0
	v_mov_b32_e32 v115, v0
	v_mov_b32_e32 v116, v0
	v_mov_b32_e32 v117, v0
	v_mov_b32_e32 v118, v0
	v_mov_b32_e32 v119, v0
	v_mov_b32_e32 v72, v0
	v_mov_b32_e32 v73, v0
	v_mov_b32_e32 v74, v0
	v_mov_b32_e32 v75, v0
	v_mov_b32_e32 v76, v0
	v_mov_b32_e32 v77, v0
	v_mov_b32_e32 v78, v0
	v_mov_b32_e32 v79, v0
	v_mov_b32_e32 v88, v0
	v_mov_b32_e32 v89, v0
	v_mov_b32_e32 v90, v0
	v_mov_b32_e32 v91, v0
	v_mov_b32_e32 v92, v0
	v_mov_b32_e32 v93, v0
	v_mov_b32_e32 v94, v0
	v_mov_b32_e32 v95, v0
	v_mov_b32_e32 v104, v0
	v_mov_b32_e32 v105, v0
	v_mov_b32_e32 v106, v0
	v_mov_b32_e32 v107, v0
	v_mov_b32_e32 v108, v0
	v_mov_b32_e32 v109, v0
	v_mov_b32_e32 v110, v0
	v_mov_b32_e32 v111, v0
	v_mov_b32_e32 v120, v0
	v_mov_b32_e32 v121, v0
	v_mov_b32_e32 v122, v0
	v_mov_b32_e32 v123, v0
	v_mov_b32_e32 v124, v0
	v_mov_b32_e32 v125, v0
	v_mov_b32_e32 v126, v0
	v_mov_b32_e32 v127, v0
	.p2align	6

; template <class Epi, class Sched, bool F8 = false>
; __device__ __forceinline__ void gemm_phase(LAS unsigned char* lds, const int lda, const int ldb, const Sched& S, const Epi& E) {
;     ...
;         for (int t = 0; t < nt; t += 2) {
;             const bool last = (t == nt - 2);
;             const char* a1 = cA + (size_t)(t + 1) * kstep;
;             const char* a2 = last ? nA : cA + (size_t)(t + 2) * kstep; const char* b2 = last ? nB : cB + (size_t)(t + 2) * kstepB;
;             const char* a3 = a2 + kstep; const char* b3 = b2 + kstepB;
;     ...
;         if (!(Epi::KEEP && cur.kind == 0)) {
; #pragma unroll
;         for (int a = 0; a < 2; ++a)
; #pragma unroll
;             for (int b = 0; b < 2; ++b)
; #pragma unroll
;                 for (int m = 0; m < 4; ++m)
; #pragma unroll
;                     for (int n = 0; n < 2; ++n) acc[a][b][m][n] = (f32x4){0.f, 0.f, 0.f, 0.f};
;         }
;         cur = nxt; cA = nA; cB = nB; ++ui;
.LBB0_407:
	s_add_i32 s62, s9, -2
	s_add_u32 s63, s18, 0x10000
	s_addc_u32 vcc_lo, s19, 0
	s_add_u32 vcc_hi, s16, 0x80080
	v_mov_b32_e32 v0, 0
	s_addc_u32 s35, s17, 0
	s_mov_b32 s4, 0
	v_mov_b32_e32 v1, v0
	v_mov_b32_e32 v2, v0
	v_mov_b32_e32 v3, v0
	v_mov_b32_e32 v4, v0
	v_mov_b32_e32 v5, v0
	v_mov_b32_e32 v6, v0
	v_mov_b32_e32 v7, v0
	v_mov_b32_e32 v8, v0
	v_mov_b32_e32 v9, v0
	v_mov_b32_e32 v10, v0
	v_mov_b32_e32 v11, v0
	v_mov_b32_e32 v12, v0
	v_mov_b32_e32 v13, v0
	v_mov_b32_e32 v14, v0
	v_mov_b32_e32 v15, v0
	v_mov_b32_e32 v16, v0
	v_mov_b32_e32 v17, v0
	v_mov_b32_e32 v18, v0
	v_mov_b32_e32 v19, v0
	v_mov_b32_e32 v20, v0
	v_mov_b32_e32 v21, v0
	v_mov_b32_e32 v22, v0
	v_mov_b32_e32 v23, v0
	v_mov_b32_e32 v24, v0
	v_mov_b32_e32 v25, v0
	v_mov_b32_e32 v26, v0
	v_mov_b32_e32 v27, v0
	v_mov_b32_e32 v28, v0
	v_mov_b32_e32 v29, v0
	v_mov_b32_e32 v30, v0
	v_mov_b32_e32 v31, v0
	v_mov_b32_e32 v64, v0
	v_mov_b32_e32 v65, v0
	v_mov_b32_e32 v66, v0
	v_mov_b32_e32 v67, v0
	v_mov_b32_e32 v68, v0
	v_mov_b32_e32 v69, v0
	v_mov_b32_e32 v70, v0
	v_mov_b32_e32 v71, v0
	v_mov_b32_e32 v72, v0
	v_mov_b32_e32 v73, v0
	v_mov_b32_e32 v74, v0
	v_mov_b32_e32 v75, v0
	v_mov_b32_e32 v76, v0
	v_mov_b32_e32 v77, v0
	v_mov_b32_e32 v78, v0
	v_mov_b32_e32 v79, v0
	v_mov_b32_e32 v80, v0
	v_mov_b32_e32 v81, v0
	v_mov_b32_e32 v82, v0
	v_mov_b32_e32 v83, v0
	v_mov_b32_e32 v84, v0
	v_mov_b32_e32 v85, v0
	v_mov_b32_e32 v86, v0
	v_mov_b32_e32 v87, v0
	v_mov_b32_e32 v88, v0
	v_mov_b32_e32 v89, v0
	v_mov_b32_e32 v90, v0
	v_mov_b32_e32 v91, v0
	v_mov_b32_e32 v92, v0
	v_mov_b32_e32 v93, v0
	v_mov_b32_e32 v94, v0
	v_mov_b32_e32 v95, v0
	v_mov_b32_e32 v32, v0
	v_mov_b32_e32 v33, v0
	v_mov_b32_e32 v34, v0
	v_mov_b32_e32 v35, v0
	v_mov_b32_e32 v36, v0
	v_mov_b32_e32 v37, v0
	v_mov_b32_e32 v38, v0
	v_mov_b32_e32 v39, v0
	v_mov_b32_e32 v40, v0
	v_mov_b32_e32 v41, v0
	v_mov_b32_e32 v42, v0
	v_mov_b32_e32 v43, v0
	v_mov_b32_e32 v44, v0
	v_mov_b32_e32 v45, v0
	v_mov_b32_e32 v46, v0
	v_mov_b32_e32 v47, v0
	v_mov_b32_e32 v48, v0
	v_mov_b32_e32 v49, v0
	v_mov_b32_e32 v50, v0
	v_mov_b32_e32 v51, v0
	v_mov_b32_e32 v52, v0
	v_mov_b32_e32 v53, v0
	v_mov_b32_e32 v54, v0
	v_mov_b32_e32 v55, v0
	v_mov_b32_e32 v56, v0
	v_mov_b32_e32 v57, v0
	v_mov_b32_e32 v58, v0
	v_mov_b32_e32 v59, v0
	v_mov_b32_e32 v60, v0
	v_mov_b32_e32 v61, v0
	v_mov_b32_e32 v62, v0
	v_mov_b32_e32 v63, v0
	v_mov_b32_e32 v96, v0
	v_mov_b32_e32 v97, v0
	v_mov_b32_e32 v98, v0
	v_mov_b32_e32 v99, v0
	v_mov_b32_e32 v100, v0
	v_mov_b32_e32 v101, v0
	v_mov_b32_e32 v102, v0
	v_mov_b32_e32 v103, v0
	v_mov_b32_e32 v112, v0
	v_mov_b32_e32 v113, v0
	v_mov_b32_e32 v114, v0
	v_mov_b32_e32 v115, v0
	v_mov_b32_e32 v116, v0
	v_mov_b32_e32 v117, v0
	v_mov_b32_e32 v118, v0
	v_mov_b32_e32 v119, v0
	v_mov_b32_e32 v120, v0
	v_mov_b32_e32 v121, v0
	v_mov_b32_e32 v122, v0
	v_mov_b32_e32 v123, v0
	v_mov_b32_e32 v124, v0
	v_mov_b32_e32 v125, v0
	v_mov_b32_e32 v126, v0
	v_mov_b32_e32 v127, v0
	v_mov_b32_e32 v128, v0
	v_mov_b32_e32 v129, v0
	v_mov_b32_e32 v130, v0
	v_mov_b32_e32 v131, v0
	v_mov_b32_e32 v132, v0
	v_mov_b32_e32 v133, v0
	v_mov_b32_e32 v134, v0
	v_mov_b32_e32 v135, v0
	.p2align	6

; template <class Epi, class Sched, bool F8 = false>
; __device__ __forceinline__ void gemm_phase(LAS unsigned char* lds, const int lda, const int ldb, const Sched& S, const Epi& E) {
;     ...
;         for (int t = 0; t < nt; t += 2) {
;             const bool last = (t == nt - 2);
;             const char* a1 = cA + (size_t)(t + 1) * kstep;
;             const char* a2 = last ? nA : cA + (size_t)(t + 2) * kstep; const char* b2 = last ? nB : cB + (size_t)(t + 2) * kstepB;
;             const char* a3 = a2 + kstep; const char* b3 = b2 + kstepB;
.LBB0_484:
	s_add_u32 s9, s18, 0x10000
	s_addc_u32 s33, s19, 0
	s_add_u32 s47, s16, 0x80080
	s_addc_u32 s62, s17, 0
	s_mov_b32 s63, -2
	.p2align	6

; template <class Epi, class Sched, bool F8 = false>
; __device__ __forceinline__ void gemm_phase(LAS unsigned char* lds, const int lda, const int ldb, const Sched& S, const Epi& E) {
;     ...
;         for (int t = 0; t < nt; t += 2) {
;             const bool last = (t == nt - 2);
;             const char* a1 = cA + (size_t)(t + 1) * kstep;
;             const char* a2 = last ? nA : cA + (size_t)(t + 2) * kstep; const char* b2 = last ? nB : cB + (size_t)(t + 2) * kstepB;
;             const char* a3 = a2 + kstep; const char* b3 = b2 + kstepB;
;     ...
;         if (!(Epi::KEEP && cur.kind == 0)) {
; #pragma unroll
;         for (int a = 0; a < 2; ++a)
; #pragma unroll
;             for (int b = 0; b < 2; ++b)
; #pragma unroll
;                 for (int m = 0; m < 4; ++m)
; #pragma unroll
;                     for (int n = 0; n < 2; ++n) acc[a][b][m][n] = (f32x4){0.f, 0.f, 0.f, 0.f};
;         }
;         cur = nxt; cA = nA; cB = nB; ++ui;
.LBB0_631:
	s_add_u32 s51, s18, 0x10000
	s_addc_u32 s67, s19, 0
	s_add_u32 vcc_lo, s16, 0x100080
	v_mov_b32_e32 v0, 0
	s_addc_u32 vcc_hi, s17, 0
	s_mov_b32 s64, -2
	v_mov_b32_e32 v1, v0
	v_mov_b32_e32 v2, v0
	v_mov_b32_e32 v3, v0
	v_mov_b32_e32 v4, v0
	s_waitcnt lgkmcnt(0)
	v_mov_b32_e32 v5, v0
	v_mov_b32_e32 v6, v0
	v_mov_b32_e32 v7, v0
	v_mov_b32_e32 v16, v0
	v_mov_b32_e32 v17, v0
	v_mov_b32_e32 v18, v0
	v_mov_b32_e32 v19, v0
	v_mov_b32_e32 v20, v0
	v_mov_b32_e32 v21, v0
	v_mov_b32_e32 v22, v0
	v_mov_b32_e32 v23, v0
	v_mov_b32_e32 v32, v0
	v_mov_b32_e32 v33, v0
	v_mov_b32_e32 v34, v0
	v_mov_b32_e32 v35, v0
	v_mov_b32_e32 v36, v0
	v_mov_b32_e32 v37, v0
	v_mov_b32_e32 v38, v0
	v_mov_b32_e32 v39, v0
	v_mov_b32_e32 v48, v0
	v_mov_b32_e32 v49, v0
	v_mov_b32_e32 v50, v0
	v_mov_b32_e32 v51, v0
	v_mov_b32_e32 v52, v0
	v_mov_b32_e32 v53, v0
	v_mov_b32_e32 v54, v0
	v_mov_b32_e32 v55, v0
	v_mov_b32_e32 v8, v0
	v_mov_b32_e32 v9, v0
	v_mov_b32_e32 v10, v0
	v_mov_b32_e32 v11, v0
	v_mov_b32_e32 v12, v0
	v_mov_b32_e32 v13, v0
	v_mov_b32_e32 v14, v0
	v_mov_b32_e32 v15, v0
	v_mov_b32_e32 v24, v0
	v_mov_b32_e32 v25, v0
	v_mov_b32_e32 v26, v0
	v_mov_b32_e32 v27, v0
	v_mov_b32_e32 v28, v0
	v_mov_b32_e32 v29, v0
	v_mov_b32_e32 v30, v0
	v_mov_b32_e32 v31, v0
	v_mov_b32_e32 v40, v0
	v_mov_b32_e32 v41, v0
	v_mov_b32_e32 v42, v0
	v_mov_b32_e32 v43, v0
	v_mov_b32_e32 v44, v0
	v_mov_b32_e32 v45, v0
	v_mov_b32_e32 v46, v0
	v_mov_b32_e32 v47, v0
	v_mov_b32_e32 v56, v0
	v_mov_b32_e32 v57, v0
	v_mov_b32_e32 v58, v0
	v_mov_b32_e32 v59, v0
	v_mov_b32_e32 v60, v0
	v_mov_b32_e32 v61, v0
	v_mov_b32_e32 v62, v0
	v_mov_b32_e32 v63, v0
	v_mov_b32_e32 v64, v0
	v_mov_b32_e32 v65, v0
	v_mov_b32_e32 v66, v0
	v_mov_b32_e32 v67, v0
	v_mov_b32_e32 v68, v0
	v_mov_b32_e32 v69, v0
	v_mov_b32_e32 v70, v0
	v_mov_b32_e32 v71, v0
	v_mov_b32_e32 v80, v0
	v_mov_b32_e32 v81, v0
	v_mov_b32_e32 v82, v0
	v_mov_b32_e32 v83, v0
	v_mov_b32_e32 v84, v0
	v_mov_b32_e32 v85, v0
	v_mov_b32_e32 v86, v0
	v_mov_b32_e32 v87, v0
	v_mov_b32_e32 v96, v0
	v_mov_b32_e32 v97, v0
	v_mov_b32_e32 v98, v0
	v_mov_b32_e32 v99, v0
	v_mov_b32_e32 v100, v0
	v_mov_b32_e32 v101, v0
	v_mov_b32_e32 v102, v0
	v_mov_b32_e32 v103, v0
	v_mov_b32_e32 v112, v0
	v_mov_b32_e32 v113, v0
	v_mov_b32_e32 v114, v0
	v_mov_b32_e32 v115, v0
	v_mov_b32_e32 v116, v0
	v_mov_b32_e32 v117, v0
	v_mov_b32_e32 v118, v0
	v_mov_b32_e32 v119, v0
	v_mov_b32_e32 v72, v0
	v_mov_b32_e32 v73, v0
	v_mov_b32_e32 v74, v0
	v_mov_b32_e32 v75, v0
	v_mov_b32_e32 v76, v0
	v_mov_b32_e32 v77, v0
	v_mov_b32_e32 v78, v0
	v_mov_b32_e32 v79, v0
	v_mov_b32_e32 v88, v0
	v_mov_b32_e32 v89, v0
	v_mov_b32_e32 v90, v0
	v_mov_b32_e32 v91, v0
	v_mov_b32_e32 v92, v0
	v_mov_b32_e32 v93, v0
	v_mov_b32_e32 v94, v0
	v_mov_b32_e32 v95, v0
	v_mov_b32_e32 v104, v0
	v_mov_b32_e32 v105, v0
	v_mov_b32_e32 v106, v0
	v_mov_b32_e32 v107, v0
	v_mov_b32_e32 v108, v0
	v_mov_b32_e32 v109, v0
	v_mov_b32_e32 v110, v0
	v_mov_b32_e32 v111, v0
	v_mov_b32_e32 v120, v0
	v_mov_b32_e32 v121, v0
	v_mov_b32_e32 v122, v0
	v_mov_b32_e32 v123, v0
	v_mov_b32_e32 v124, v0
	v_mov_b32_e32 v125, v0
	v_mov_b32_e32 v126, v0
	v_mov_b32_e32 v127, v0
	.p2align	6

; template <class Epi, class Sched, bool F8 = false>
; __device__ __forceinline__ void gemm_phase(LAS unsigned char* lds, const int lda, const int ldb, const Sched& S, const Epi& E) {
;     ...
;         for (int t = 0; t < nt; t += 2) {
;             const bool last = (t == nt - 2);
;             const char* a1 = cA + (size_t)(t + 1) * kstep;
;             const char* a2 = last ? nA : cA + (size_t)(t + 2) * kstep; const char* b2 = last ? nB : cB + (size_t)(t + 2) * kstepB;
;             const char* a3 = a2 + kstep; const char* b3 = b2 + kstepB;
;     ...
;         if (!(Epi::KEEP && cur.kind == 0)) {
; #pragma unroll
;         for (int a = 0; a < 2; ++a)
; #pragma unroll
;             for (int b = 0; b < 2; ++b)
; #pragma unroll
;                 for (int m = 0; m < 4; ++m)
; #pragma unroll
;                     for (int n = 0; n < 2; ++n) acc[a][b][m][n] = (f32x4){0.f, 0.f, 0.f, 0.f};
;         }
;         cur = nxt; cA = nA; cB = nB; ++ui;
.LBB0_777:
	s_add_u32 s8, s6, 0x10000
	s_addc_u32 s9, s7, 0
	s_add_u32 s33, s4, 0x100080
	v_mov_b32_e32 v0, 0
	s_addc_u32 s43, s5, 0
	s_mov_b32 s45, -2
	v_mov_b32_e32 v1, v0
	v_mov_b32_e32 v2, v0
	v_mov_b32_e32 v3, v0
	v_mov_b32_e32 v64, v0
	v_mov_b32_e32 v65, v0
	v_mov_b32_e32 v66, v0
	v_mov_b32_e32 v67, v0
	v_mov_b32_e32 v8, v0
	v_mov_b32_e32 v9, v0
	v_mov_b32_e32 v10, v0
	v_mov_b32_e32 v11, v0
	v_mov_b32_e32 v68, v0
	v_mov_b32_e32 v69, v0
	v_mov_b32_e32 v70, v0
	v_mov_b32_e32 v71, v0
	v_mov_b32_e32 v16, v0
	v_mov_b32_e32 v17, v0
	v_mov_b32_e32 v18, v0
	v_mov_b32_e32 v19, v0
	v_mov_b32_e32 v80, v0
	v_mov_b32_e32 v81, v0
	v_mov_b32_e32 v82, v0
	v_mov_b32_e32 v83, v0
	v_mov_b32_e32 v24, v0
	v_mov_b32_e32 v25, v0
	v_mov_b32_e32 v26, v0
	v_mov_b32_e32 v27, v0
	v_mov_b32_e32 v88, v0
	v_mov_b32_e32 v89, v0
	v_mov_b32_e32 v90, v0
	v_mov_b32_e32 v91, v0
	v_mov_b32_e32 v4, v0
	v_mov_b32_e32 v5, v0
	v_mov_b32_e32 v6, v0
	v_mov_b32_e32 v7, v0
	v_mov_b32_e32 v72, v0
	v_mov_b32_e32 v73, v0
	v_mov_b32_e32 v74, v0
	v_mov_b32_e32 v75, v0
	v_mov_b32_e32 v12, v0
	v_mov_b32_e32 v13, v0
	v_mov_b32_e32 v14, v0
	v_mov_b32_e32 v15, v0
	v_mov_b32_e32 v76, v0
	v_mov_b32_e32 v77, v0
	v_mov_b32_e32 v78, v0
	v_mov_b32_e32 v79, v0
	v_mov_b32_e32 v20, v0
	v_mov_b32_e32 v21, v0
	v_mov_b32_e32 v22, v0
	v_mov_b32_e32 v23, v0
	v_mov_b32_e32 v84, v0
	v_mov_b32_e32 v85, v0
	v_mov_b32_e32 v86, v0
	v_mov_b32_e32 v87, v0
	v_mov_b32_e32 v28, v0
	v_mov_b32_e32 v29, v0
	v_mov_b32_e32 v30, v0
	v_mov_b32_e32 v31, v0
	v_mov_b32_e32 v92, v0
	v_mov_b32_e32 v93, v0
	v_mov_b32_e32 v94, v0
	v_mov_b32_e32 v95, v0
	v_mov_b32_e32 v32, v0
	v_mov_b32_e32 v33, v0
	v_mov_b32_e32 v34, v0
	v_mov_b32_e32 v35, v0
	v_mov_b32_e32 v96, v0
	v_mov_b32_e32 v97, v0
	v_mov_b32_e32 v98, v0
	v_mov_b32_e32 v99, v0
	v_mov_b32_e32 v40, v0
	v_mov_b32_e32 v41, v0
	v_mov_b32_e32 v42, v0
	v_mov_b32_e32 v43, v0
	v_mov_b32_e32 v100, v0
	v_mov_b32_e32 v101, v0
	v_mov_b32_e32 v102, v0
	v_mov_b32_e32 v103, v0
	v_mov_b32_e32 v48, v0
	v_mov_b32_e32 v49, v0
	v_mov_b32_e32 v50, v0
	v_mov_b32_e32 v51, v0
	v_mov_b32_e32 v126, v0
	v_mov_b32_e32 v127, v0
	v_mov_b32_e32 v128, v0
	v_mov_b32_e32 v129, v0
	v_mov_b32_e32 v56, v0
	v_mov_b32_e32 v57, v0
	v_mov_b32_e32 v58, v0
	v_mov_b32_e32 v59, v0
	v_mov_b32_e32 v104, v0
	v_mov_b32_e32 v105, v0
	v_mov_b32_e32 v106, v0
	v_mov_b32_e32 v107, v0
	v_mov_b32_e32 v36, v0
	v_mov_b32_e32 v37, v0
	v_mov_b32_e32 v38, v0
	v_mov_b32_e32 v39, v0
	v_mov_b32_e32 v110, v0
	v_mov_b32_e32 v111, v0
	v_mov_b32_e32 v112, v0
	v_mov_b32_e32 v113, v0
	v_mov_b32_e32 v44, v0
	v_mov_b32_e32 v45, v0
	v_mov_b32_e32 v46, v0
	v_mov_b32_e32 v47, v0
	v_mov_b32_e32 v114, v0
	v_mov_b32_e32 v115, v0
	v_mov_b32_e32 v116, v0
	v_mov_b32_e32 v117, v0
	v_mov_b32_e32 v52, v0
	v_mov_b32_e32 v53, v0
	v_mov_b32_e32 v54, v0
	v_mov_b32_e32 v55, v0
	v_mov_b32_e32 v154, v0
	v_mov_b32_e32 v155, v0
	v_mov_b32_e32 v156, v0
	v_mov_b32_e32 v157, v0
	v_mov_b32_e32 v60, v0
	v_mov_b32_e32 v61, v0
	v_mov_b32_e32 v62, v0
	v_mov_b32_e32 v63, v0
	v_mov_b32_e32 v158, v0
	v_mov_b32_e32 v159, v0
	v_mov_b32_e32 v160, v0
	v_mov_b32_e32 v161, v0
	.p2align	6

; template <class Epi, class Sched, bool F8 = false>
; __device__ __forceinline__ void gemm_phase(LAS unsigned char* lds, const int lda, const int ldb, const Sched& S, const Epi& E) {
;     ...
;         for (int t = 0; t < nt; t += 2) {
;             const bool last = (t == nt - 2);
;             const char* a1 = cA + (size_t)(t + 1) * kstep;
;             const char* a2 = last ? nA : cA + (size_t)(t + 2) * kstep; const char* b2 = last ? nB : cB + (size_t)(t + 2) * kstepB;
;             const char* a3 = a2 + kstep; const char* b3 = b2 + kstepB;
;     ...
;         if (!(Epi::KEEP && cur.kind == 0)) {
; #pragma unroll
;         for (int a = 0; a < 2; ++a)
; #pragma unroll
;             for (int b = 0; b < 2; ++b)
; #pragma unroll
;                 for (int m = 0; m < 4; ++m)
; #pragma unroll
;                     for (int n = 0; n < 2; ++n) acc[a][b][m][n] = (f32x4){0.f, 0.f, 0.f, 0.f};
;         }
;         cur = nxt; cA = nA; cB = nB; ++ui;
.LBB0_934:
	s_add_u32 s89, s14, 0x10000
	s_addc_u32 s90, s15, 0
	s_add_u32 s91, s12, 0x2b0080
	v_mov_b32_e32 v0, 0
	s_addc_u32 s92, s13, 0
	s_mov_b32 s64, -2
	v_mov_b32_e32 v1, v0
	v_mov_b32_e32 v2, v0
	v_mov_b32_e32 v3, v0
	v_mov_b32_e32 v4, v0
	s_waitcnt lgkmcnt(0)
	v_mov_b32_e32 v5, v0
	v_mov_b32_e32 v6, v0
	v_mov_b32_e32 v7, v0
	v_mov_b32_e32 v16, v0
	v_mov_b32_e32 v17, v0
	v_mov_b32_e32 v18, v0
	v_mov_b32_e32 v19, v0
	v_mov_b32_e32 v20, v0
	v_mov_b32_e32 v21, v0
	v_mov_b32_e32 v22, v0
	v_mov_b32_e32 v23, v0
	v_mov_b32_e32 v32, v0
	v_mov_b32_e32 v33, v0
	v_mov_b32_e32 v34, v0
	v_mov_b32_e32 v35, v0
	v_mov_b32_e32 v36, v0
	v_mov_b32_e32 v37, v0
	v_mov_b32_e32 v38, v0
	v_mov_b32_e32 v39, v0
	v_mov_b32_e32 v48, v0
	v_mov_b32_e32 v49, v0
	v_mov_b32_e32 v50, v0
	v_mov_b32_e32 v51, v0
	v_mov_b32_e32 v52, v0
	v_mov_b32_e32 v53, v0
	v_mov_b32_e32 v54, v0
	v_mov_b32_e32 v55, v0
	v_mov_b32_e32 v8, v0
	v_mov_b32_e32 v9, v0
	v_mov_b32_e32 v10, v0
	v_mov_b32_e32 v11, v0
	v_mov_b32_e32 v12, v0
	v_mov_b32_e32 v13, v0
	v_mov_b32_e32 v14, v0
	v_mov_b32_e32 v15, v0
	v_mov_b32_e32 v24, v0
	v_mov_b32_e32 v25, v0
	v_mov_b32_e32 v26, v0
	v_mov_b32_e32 v27, v0
	v_mov_b32_e32 v28, v0
	v_mov_b32_e32 v29, v0
	v_mov_b32_e32 v30, v0
	v_mov_b32_e32 v31, v0
	v_mov_b32_e32 v40, v0
	v_mov_b32_e32 v41, v0
	v_mov_b32_e32 v42, v0
	v_mov_b32_e32 v43, v0
	v_mov_b32_e32 v44, v0
	v_mov_b32_e32 v45, v0
	v_mov_b32_e32 v46, v0
	v_mov_b32_e32 v47, v0
	v_mov_b32_e32 v56, v0
	v_mov_b32_e32 v57, v0
	v_mov_b32_e32 v58, v0
	v_mov_b32_e32 v59, v0
	v_mov_b32_e32 v60, v0
	v_mov_b32_e32 v61, v0
	v_mov_b32_e32 v62, v0
	v_mov_b32_e32 v63, v0
	v_mov_b32_e32 v64, v0
	v_mov_b32_e32 v65, v0
	v_mov_b32_e32 v66, v0
	v_mov_b32_e32 v67, v0
	v_mov_b32_e32 v68, v0
	v_mov_b32_e32 v69, v0
	v_mov_b32_e32 v70, v0
	v_mov_b32_e32 v71, v0
	v_mov_b32_e32 v80, v0
	v_mov_b32_e32 v81, v0
	v_mov_b32_e32 v82, v0
	v_mov_b32_e32 v83, v0
	v_mov_b32_e32 v84, v0
	v_mov_b32_e32 v85, v0
	v_mov_b32_e32 v86, v0
	v_mov_b32_e32 v87, v0
	v_mov_b32_e32 v96, v0
	v_mov_b32_e32 v97, v0
	v_mov_b32_e32 v98, v0
	v_mov_b32_e32 v99, v0
	v_mov_b32_e32 v100, v0
	v_mov_b32_e32 v101, v0
	v_mov_b32_e32 v102, v0
	v_mov_b32_e32 v103, v0
	v_mov_b32_e32 v112, v0
	v_mov_b32_e32 v113, v0
	v_mov_b32_e32 v114, v0
	v_mov_b32_e32 v115, v0
	v_mov_b32_e32 v116, v0
	v_mov_b32_e32 v117, v0
	v_mov_b32_e32 v118, v0
	v_mov_b32_e32 v119, v0
	v_mov_b32_e32 v72, v0
	v_mov_b32_e32 v73, v0
	v_mov_b32_e32 v74, v0
	v_mov_b32_e32 v75, v0
	v_mov_b32_e32 v76, v0
	v_mov_b32_e32 v77, v0
	v_mov_b32_e32 v78, v0
	v_mov_b32_e32 v79, v0
	v_mov_b32_e32 v88, v0
	v_mov_b32_e32 v89, v0
	v_mov_b32_e32 v90, v0
	v_mov_b32_e32 v91, v0
	v_mov_b32_e32 v92, v0
	v_mov_b32_e32 v93, v0
	v_mov_b32_e32 v94, v0
	v_mov_b32_e32 v95, v0
	v_mov_b32_e32 v104, v0
	v_mov_b32_e32 v105, v0
	v_mov_b32_e32 v106, v0
	v_mov_b32_e32 v107, v0
	v_mov_b32_e32 v108, v0
	v_mov_b32_e32 v109, v0
	v_mov_b32_e32 v110, v0
	v_mov_b32_e32 v111, v0
	v_mov_b32_e32 v120, v0
	v_mov_b32_e32 v121, v0
	v_mov_b32_e32 v122, v0
	v_mov_b32_e32 v123, v0
	v_mov_b32_e32 v124, v0
	v_mov_b32_e32 v125, v0
	v_mov_b32_e32 v126, v0
	v_mov_b32_e32 v127, v0
	.p2align	6
